# v10 plus attention PV accumulators updated in place (per-iteration accumulator copies and the MFMA-to-VALU pad removed)
# speedup vs baseline: 1.0017x; 1.0017x over previous
; __device__ __forceinline__ void attn_phase(const bf16* Q, const bf16* K, const bf16* V, bf16* O, int gw, int ngw, int lane) {
;     ...
;         ATT_LOAD(t0 + 14)
;         for (int s_hi = t0 + 14; s_hi >= 0; s_hi -= 16) {
;             const bf16x8 ka0 = kn0, ka1 = kn1;
;             unsigned short vv[4][4];
; #pragma unroll
;             for (int j = 0; j < 4; ++j)
; #pragma unroll
;                 for (int dt = 0; dt < 4; ++dt) vv[dt][j] = vn[dt][j];
;             ATT_LOAD(s_hi - 16)
;             f32x4 z = (f32x4){0.f, 0.f, 0.f, 0.f};
;             z = __builtin_amdgcn_mfma_f32_16x16x32_bf16(ka0, qb0, z, 0, 0, 0);
;             z = __builtin_amdgcn_mfma_f32_16x16x32_bf16(ka1, qb1, z, 0, 0, 0);
;             float dd[4], sg[4];
; #pragma unroll
;             for (int i = 0; i < 4; ++i) {
;                 const int s = s_hi - (4 * fq + i);
;                 const bool valid = (s >= 0) && (s < tq);
;                 const float e = __builtin_amdgcn_exp2f(fminf(z[i], 100.f));
;                 const float d = __builtin_amdgcn_rcpf(1.0f + e);
;                 dd[i] = valid ? d : 1.f; sg[i] = valid ? e * d : 0.f;
;             }
;             const float c1 = dd[0], c2 = c1 * dd[1], c3 = c2 * dd[2], g = c3 * dd[3];
;             const float g0 = __shfl(g, fr), g1 = __shfl(g, fr + 16), g2 = __shfl(g, fr + 32), g3 = __shfl(g, fr + 48);
;             float pre = carry;
;             if (fq > 0) pre *= g0;
;             if (fq > 1) pre *= g1;
;             if (fq > 2) pre *= g2;
;             carry = carry * ((g0 * g1) * (g2 * g3));
;             const float p0 = sg[0] * pre, p1 = sg[1] * (pre * c1), p2 = sg[2] * (pre * c2), p3 = sg[3] * (pre * c3);
;             bf16x8 pb; { const unsigned w0 = pk2(p0, p1), w1 = pk2(p2, p3); pb[0] = (short)(w0 & 0xffff); pb[1] = (short)(w0 >> 16); pb[2] = (short)(w1 & 0xffff); pb[3] = (short)(w1 >> 16); pb[4] = 0; pb[5] = 0; pb[6] = 0; pb[7] = 0; }
; #pragma unroll
;             for (int dt = 0; dt < 4; ++dt) {
;                 bf16x8 va; va[0] = (short)vv[dt][0]; va[1] = (short)vv[dt][1]; va[2] = (short)vv[dt][2]; va[3] = (short)vv[dt][3]; va[4] = 0; va[5] = 0; va[6] = 0; va[7] = 0;
;                 o[dt] = __builtin_amdgcn_mfma_f32_16x16x32_bf16(va, pb, o[dt], 0, 0, 0);
;             }
;             if (__builtin_amdgcn_ballot_w64(carry != 0.f) == 0ull) break;
.LBB0_2225:
	v_mov_b32_e32 v73, v236
	v_lshl_add_u64 v[0:1], s[4:5], 0, v[72:73]
	v_lshlrev_b64 v[0:1], 11, v[0:1]
	v_lshlrev_b64 v[4:5], 11, v[68:69]
	v_lshl_add_u64 v[0:1], v[60:61], 0, v[0:1]
	v_lshlrev_b64 v[2:3], 11, v[70:71]
	v_lshl_add_u64 v[32:33], v[60:61], 0, v[4:5]
	v_lshlrev_b64 v[4:5], 11, v[66:67]
	v_lshl_add_u64 v[2:3], v[60:61], 0, v[2:3]
	v_lshl_add_u64 v[34:35], v[60:61], 0, v[4:5]
	global_load_ushort v55, v[0:1], off offset:96
	global_load_ushort v73, v[2:3], off offset:96
	global_load_ushort v82, v[32:33], off offset:96
	global_load_ushort v83, v[34:35], off offset:96
	global_load_ushort v8, v[0:1], off offset:64
	global_load_ushort v9, v[2:3], off offset:64
	global_load_ushort v10, v[32:33], off offset:64
	global_load_ushort v11, v[34:35], off offset:64
	global_load_ushort v4, v[0:1], off offset:32
	global_load_ushort v5, v[2:3], off offset:32
	global_load_ushort v6, v[32:33], off offset:32
	global_load_ushort v7, v[34:35], off offset:32
	s_nop 0
	global_load_ushort v0, v[0:1], off
	s_nop 0
	global_load_ushort v1, v[2:3], off
	global_load_ushort v92, v[32:33], off
	global_load_ushort v93, v[34:35], off
	s_add_i32 s12, s11, -16
	v_add_u32_e32 v2, s12, v78
	v_max_i32_e32 v2, 0, v2
	v_mov_b32_e32 v3, v236
	v_lshl_add_u64 v[2:3], s[4:5], 0, v[2:3]
	v_lshlrev_b64 v[2:3], 11, v[2:3]
	v_add_u32_e32 v32, s11, v77
	v_lshl_add_u64 v[64:65], v[62:63], 0, v[2:3]
	v_add_u32_e32 v2, -16, v32
	v_max_i32_e32 v2, 0, v2
	v_mov_b32_e32 v3, v236
	v_lshl_add_u64 v[66:67], s[4:5], 0, v[2:3]
	v_subrev_u32_e32 v2, 17, v32
	v_max_i32_e32 v2, 0, v2
	v_lshl_add_u64 v[68:69], s[4:5], 0, v[2:3]
	v_add_u32_e32 v2, s12, v76
	v_max_i32_e32 v2, 0, v2
	v_lshl_add_u64 v[70:71], s[4:5], 0, v[2:3]
	v_add_u32_e32 v2, s12, v75
	v_max_i32_e32 v72, 0, v2
	v_cmp_lt_u32_e32 vcc, v32, v58
	v_sub_u32_e32 v35, s11, v50
	v_cmp_lt_u32_e64 s[44:45], v35, v58
	s_pack_ll_b32_b16 s6, 0, 0
	v_mov_b32_e32 v237, v236
	s_mov_b64 s[8:9], 0
	s_waitcnt vmcnt(16)
	v_mfma_f32_16x16x32_bf16 v[84:87], v[106:109], v[36:39], 0
	v_mfma_f32_16x16x32_bf16 v[84:87], v[110:113], v[40:43], v[84:87]
	global_load_dwordx4 v[106:109], v[64:65], off
	global_load_dwordx4 v[110:113], v[64:65], off offset:64
	s_nop 7
	v_max_f32_e32 v2, v84, v84
	v_min_f32_e32 v2, 0x42c80000, v2
	v_exp_f32_e32 v2, v2
	v_sub_u32_e32 v84, s11, v49
	s_mov_b32 s11, s12
	v_add_f32_e32 v3, 1.0, v2
	v_rcp_f32_e32 v3, v3
	s_nop 0
	v_mul_f32_e32 v2, v2, v3
	v_cndmask_b32_e32 v89, 0, v2, vcc
	v_add_u32_e32 v2, -1, v32
	v_cndmask_b32_e32 v88, 1.0, v3, vcc
	v_cmp_lt_u32_e32 vcc, v2, v58
	v_max_f32_e32 v2, v85, v85
	v_min_f32_e32 v2, 0x42c80000, v2
	v_exp_f32_e32 v2, v2
	v_or_b32_e32 v85, v232, v59
	v_lshlrev_b32_e32 v85, 2, v85
	v_add_f32_e32 v3, 1.0, v2
	v_rcp_f32_e32 v3, v3
	s_nop 0
	v_mul_f32_e32 v2, v2, v3
	v_cndmask_b32_e32 v90, 0, v2, vcc
	v_max_f32_e32 v2, v86, v86
	v_min_f32_e32 v2, 0x42c80000, v2
	v_exp_f32_e32 v2, v2
	v_cndmask_b32_e32 v34, 1.0, v3, vcc
	v_cmp_lt_u32_e32 vcc, v84, v51
	v_add_f32_e32 v3, 1.0, v2
	v_rcp_f32_e32 v32, v3
	v_max_f32_e32 v3, v87, v87
	v_min_f32_e32 v3, 0x42c80000, v3
	v_exp_f32_e32 v3, v3
	v_cndmask_b32_e64 v35, 1.0, v32, s[44:45]
	v_add_f32_e32 v33, 1.0, v3
	v_rcp_f32_e32 v33, v33
	s_nop 0
	v_pk_mul_f32 v[2:3], v[2:3], v[32:33]
	v_mul_f32_e32 v32, v88, v34
	v_cndmask_b32_e32 v84, 1.0, v33, vcc
	v_mul_f32_e32 v33, v35, v32
	v_mul_f32_e32 v86, v84, v33
	ds_bpermute_b32 v34, v85, v86
	ds_bpermute_b32 v84, v79, v86
	ds_bpermute_b32 v35, v80, v86
	ds_bpermute_b32 v85, v81, v86
	v_cndmask_b32_e32 v3, 0, v3, vcc
	s_waitcnt lgkmcnt(3)
	v_mul_f32_e32 v86, v53, v34
	v_cndmask_b32_e64 v86, v86, v53, s[38:39]
	s_waitcnt lgkmcnt(2)
	v_mul_f32_e32 v87, v86, v84
	v_cndmask_b32_e64 v86, v86, v87, s[40:41]
	s_waitcnt lgkmcnt(1)
	v_mul_f32_e32 v87, v86, v35
	v_cndmask_b32_e64 v86, v86, v87, s[42:43]
	s_waitcnt lgkmcnt(0)
	v_pk_mul_f32 v[34:35], v[34:35], v[84:85]
	v_mul_f32_e32 v84, v88, v86
	v_mul_f32_e32 v34, v34, v35
	v_mul_f32_e32 v35, v89, v86
	v_mul_f32_e32 v84, v90, v84
	v_pk_mul_f32 v[32:33], v[32:33], v[86:87] op_sel_hi:[1,0]
	v_cvt_pk_bf16_f32 v234, v35, v84
	s_waitcnt vmcnt(2)
	v_perm_b32 v84, v92, v93, s0
	v_perm_b32 v85, v0, v1, s0
	v_mov_b32_e32 v86, s6
	v_mov_b32_e32 v87, s6
	v_cndmask_b32_e64 v2, 0, v2, s[44:45]
	v_pk_mul_f32 v[2:3], v[2:3], v[32:33]
	v_mul_f32_e32 v53, v53, v34
	v_cvt_pk_bf16_f32 v235, v2, v3
	v_cmp_neq_f32_e32 vcc, 0, v53
	s_cmp_eq_u64 vcc, 0
	v_mfma_f32_16x16x32_bf16 v[16:19], v[84:87], v[234:237], v[16:19]
	v_perm_b32 v84, v6, v7, s0
	v_perm_b32 v85, v4, v5, s0
	s_cselect_b64 s[6:7], -1, 0
	s_nop 0
	v_mfma_f32_16x16x32_bf16 v[20:23], v[84:87], v[234:237], v[20:23]
	v_perm_b32 v84, v10, v11, s0
	v_perm_b32 v85, v8, v9, s0
	s_nop 1
	v_mfma_f32_16x16x32_bf16 v[24:27], v[84:87], v[234:237], v[24:27]
	v_perm_b32 v84, v82, v83, s0
	v_perm_b32 v85, v55, v73, s0
	s_nop 1
	v_mfma_f32_16x16x32_bf16 v[28:31], v[84:87], v[234:237], v[28:31]
	s_andn2_b64 vcc, exec, s[6:7]
	s_cbranch_vccz .LBB0_2223
	s_cmp_lt_i32 s11, 0
	s_cbranch_scc0 .LBB0_2225
	s_branch .LBB0_2223
